# diff-attention LDS tiles hand-rewritten: v_max3 tile max, lazy reference-max update (rescale O/l only when tile max exceeds reference by >8 in log2 units), in-place exp/cvt, 6-deep V-fragment prefetch
# speedup vs baseline: 1.0393x; 1.0393x over previous
; __device__ __forceinline__ unsigned cvtpk(float lo, float hi) { f32x2_t v = {lo, hi}; bf16x2_t b = __builtin_convertvector(v, bf16x2_t); return __builtin_bit_cast(unsigned, b); }
; #define MFMA32(a, b, c) __builtin_amdgcn_mfma_f32_32x32x16_bf16((a), (b), (c), 0, 0, 0)
; template <class Prov, bool MASK>
; __device__ __forceinline__ void df_tile(const Prov& P, int comp, const bf16x8 (&qf)[4], int kv0, int kvlim, int lane, float& mx, float& ls, f32x16 (&o)[4]) {
;     const int hi = lane >> 5;
;     f32x16 s[2];
; #pragma unroll
;     for (int r = 0; r < 16; ++r) { s[0][r] = 0.f; s[1][r] = 0.f; }
; #pragma unroll
;     for (int ss = 0; ss < 4; ++ss) { s[0] = MFMA32(P.kfrag(comp, 0, ss, lane), qf[ss], s[0]); s[1] = MFMA32(P.kfrag(comp, 1, ss, lane), qf[ss], s[1]); }
;     if (MASK) {
; #pragma unroll
;         for (int b2 = 0; b2 < 2; ++b2)
; #pragma unroll
;             for (int r = 0; r < 16; ++r) { const int kvp = kv0 + 32 * b2 + (r & 3) + 8 * (r >> 2) + 4 * hi; if (kvp >= kvlim) s[b2][r] = -1e30f; }
;     }
;     float m = fmaxf(s[0][0], s[1][0]);
; #pragma unroll
;     for (int r = 1; r < 16; ++r) m = fmaxf(m, fmaxf(s[0][r], s[1][r]));
;     m = fmaxf(m, __shfl_xor(m, 32));
;     const float mn = fmaxf(mx, m), al = __builtin_amdgcn_exp2f(mx - mn);
;     mx = mn;
;     float ps = 0.f;
; #pragma unroll
;     for (int b2 = 0; b2 < 2; ++b2)
; #pragma unroll
;         for (int r = 0; r < 16; ++r) { const float p = __builtin_amdgcn_exp2f(s[b2][r] - mn); s[b2][r] = p; ps += p; }
;     ls = ls * al + ps;
; #pragma unroll
;     for (int c = 0; c < 4; ++c) o[c] = o[c] * al;
; #pragma unroll
;     for (int kb = 0; kb < 4; ++kb) {
;         const int b2 = kb >> 1, r0 = 8 * (kb & 1);
;         u32x4 w; w.x = cvtpk(s[b2][r0], s[b2][r0 + 1]); w.y = cvtpk(s[b2][r0 + 2], s[b2][r0 + 3]); w.z = cvtpk(s[b2][r0 + 4], s[b2][r0 + 5]); w.w = cvtpk(s[b2][r0 + 6], s[b2][r0 + 7]);
;         const bf16x8 pf = __builtin_bit_cast(bf16x8, w);
; #pragma unroll
;         for (int c = 0; c < 4; ++c) o[c] = MFMA32(P.vfrag(kb, c, lane), pf, o[c]);
;     }
.LBB0_270:
	ds_read_b128 v[64:67], v216 offset:0
	ds_read_b128 v[68:71], v216 offset:32
	ds_read_b128 v[72:75], v216 offset:64
	ds_read_b128 v[76:79], v216 offset:96
	ds_read_b128 v[218:221], v217 offset:0
	ds_read_b128 v[222:225], v217 offset:32
	s_waitcnt lgkmcnt(5)
	v_mfma_f32_32x32x16_bf16 v[80:95], v[64:67], v[96:99], 0
	s_waitcnt lgkmcnt(4)
	v_mfma_f32_32x32x16_bf16 v[80:95], v[68:71], v[100:103], v[80:95]
	s_waitcnt lgkmcnt(3)
	v_mfma_f32_32x32x16_bf16 v[80:95], v[72:75], v[104:107], v[80:95]
	s_waitcnt lgkmcnt(2)
	v_mfma_f32_32x32x16_bf16 v[80:95], v[76:79], v[108:111], v[80:95]
	s_waitcnt lgkmcnt(1)
	v_mfma_f32_32x32x16_bf16 v[64:79], v[218:221], v[96:99], 0
	ds_read_b128 v[218:221], v217 offset:64
	s_waitcnt lgkmcnt(1)
	v_mfma_f32_32x32x16_bf16 v[64:79], v[222:225], v[100:103], v[64:79]
	ds_read_b128 v[222:225], v217 offset:96
	s_waitcnt lgkmcnt(1)
	v_mfma_f32_32x32x16_bf16 v[64:79], v[218:221], v[104:107], v[64:79]
	s_waitcnt lgkmcnt(0)
	v_mfma_f32_32x32x16_bf16 v[64:79], v[222:225], v[108:111], v[64:79]
	ds_read_b64_tr_b16 v[218:219], v200 offset:18432
	ds_read_b64_tr_b16 v[220:221], v200 offset:18944
	ds_read_b64_tr_b16 v[222:223], v200 offset:22528
	ds_read_b64_tr_b16 v[224:225], v200 offset:23040
	v_max3_f32 v171, v80, v81, v82
	v_max3_f32 v175, v83, v84, v85
	v_max3_f32 v171, v171, v86, v87
	v_max3_f32 v175, v175, v88, v89
	v_max3_f32 v171, v171, v90, v91
	v_max3_f32 v175, v175, v92, v93
	v_max3_f32 v171, v171, v94, v95
	s_nop 0
	v_max3_f32 v175, v175, v64, v65
	v_max3_f32 v171, v171, v66, v67
	v_max3_f32 v175, v175, v68, v69
	v_max3_f32 v171, v171, v70, v71
	v_max3_f32 v175, v175, v72, v73
	v_max3_f32 v171, v171, v74, v75
	v_max3_f32 v175, v175, v76, v77
	v_max3_f32 v171, v171, v78, v79
	v_max_f32_e32 v171, v171, v175
	ds_bpermute_b32 v175, v161, v171
	s_waitcnt lgkmcnt(0)
	v_max_f32_e32 v171, v171, v175
	v_sub_f32_e32 v175, v171, v173
	v_cmp_lt_f32_e32 vcc, 0x41000000, v175
	s_and_b64 vcc, exec, vcc
	s_cbranch_vccnz .Ldf0_rs
.Ldf0_go:
	v_sub_f32_e32 v80, v80, v173
	v_sub_f32_e32 v81, v81, v173
	v_sub_f32_e32 v82, v82, v173
	v_sub_f32_e32 v83, v83, v173
	v_sub_f32_e32 v84, v84, v173
	v_sub_f32_e32 v85, v85, v173
	v_sub_f32_e32 v86, v86, v173
	v_sub_f32_e32 v87, v87, v173
	v_exp_f32_e32 v80, v80
	v_exp_f32_e32 v81, v81
	v_exp_f32_e32 v82, v82
	v_exp_f32_e32 v83, v83
	v_exp_f32_e32 v84, v84
	v_exp_f32_e32 v85, v85
	v_exp_f32_e32 v86, v86
	v_exp_f32_e32 v87, v87
	v_sub_f32_e32 v88, v88, v173
	v_sub_f32_e32 v89, v89, v173
	v_sub_f32_e32 v90, v90, v173
	v_sub_f32_e32 v91, v91, v173
	v_sub_f32_e32 v92, v92, v173
	v_sub_f32_e32 v93, v93, v173
	v_sub_f32_e32 v94, v94, v173
	v_sub_f32_e32 v95, v95, v173
	v_exp_f32_e32 v88, v88
	v_exp_f32_e32 v89, v89
	v_exp_f32_e32 v90, v90
	v_exp_f32_e32 v91, v91
	v_exp_f32_e32 v92, v92
	v_exp_f32_e32 v93, v93
	v_exp_f32_e32 v94, v94
	v_exp_f32_e32 v95, v95
	v_add_f32_e32 v169, v169, v80
	v_add_f32_e32 v169, v169, v81
	v_add_f32_e32 v169, v169, v82
	v_add_f32_e32 v169, v169, v83
	v_add_f32_e32 v169, v169, v84
	v_add_f32_e32 v169, v169, v85
	v_add_f32_e32 v169, v169, v86
	v_add_f32_e32 v169, v169, v87
	v_sub_f32_e32 v64, v64, v173
	v_sub_f32_e32 v65, v65, v173
	v_sub_f32_e32 v66, v66, v173
	v_sub_f32_e32 v67, v67, v173
	v_sub_f32_e32 v68, v68, v173
	v_sub_f32_e32 v69, v69, v173
	v_sub_f32_e32 v70, v70, v173
	v_sub_f32_e32 v71, v71, v173
	v_exp_f32_e32 v64, v64
	v_exp_f32_e32 v65, v65
	v_exp_f32_e32 v66, v66
	v_exp_f32_e32 v67, v67
	v_exp_f32_e32 v68, v68
	v_exp_f32_e32 v69, v69
	v_exp_f32_e32 v70, v70
	v_exp_f32_e32 v71, v71
	v_add_f32_e32 v169, v169, v88
	v_add_f32_e32 v169, v169, v89
	v_add_f32_e32 v169, v169, v90
	v_add_f32_e32 v169, v169, v91
	v_add_f32_e32 v169, v169, v92
	v_add_f32_e32 v169, v169, v93
	v_add_f32_e32 v169, v169, v94
	v_add_f32_e32 v169, v169, v95
	v_sub_f32_e32 v72, v72, v173
	v_sub_f32_e32 v73, v73, v173
	v_sub_f32_e32 v74, v74, v173
	v_sub_f32_e32 v75, v75, v173
	v_sub_f32_e32 v76, v76, v173
	v_sub_f32_e32 v77, v77, v173
	v_sub_f32_e32 v78, v78, v173
	v_sub_f32_e32 v79, v79, v173
	v_exp_f32_e32 v72, v72
	v_exp_f32_e32 v73, v73
	v_exp_f32_e32 v74, v74
	v_exp_f32_e32 v75, v75
	v_exp_f32_e32 v76, v76
	v_exp_f32_e32 v77, v77
	v_exp_f32_e32 v78, v78
	v_exp_f32_e32 v79, v79
	v_add_f32_e32 v169, v169, v64
	v_add_f32_e32 v169, v169, v65
	v_add_f32_e32 v169, v169, v66
	v_add_f32_e32 v169, v169, v67
	v_add_f32_e32 v169, v169, v68
	v_add_f32_e32 v169, v169, v69
	v_add_f32_e32 v169, v169, v70
	v_add_f32_e32 v169, v169, v71
	v_add_f32_e32 v169, v169, v72
	v_add_f32_e32 v169, v169, v73
	v_add_f32_e32 v169, v169, v74
	v_add_f32_e32 v169, v169, v75
	v_add_f32_e32 v169, v169, v76
	v_add_f32_e32 v169, v169, v77
	v_add_f32_e32 v169, v169, v78
	v_add_f32_e32 v169, v169, v79
	v_cvt_pk_bf16_f32 v80, v80, v81
	v_cvt_pk_bf16_f32 v81, v82, v83
	v_cvt_pk_bf16_f32 v82, v84, v85
	v_cvt_pk_bf16_f32 v83, v86, v87
	v_cvt_pk_bf16_f32 v88, v88, v89
	v_cvt_pk_bf16_f32 v89, v90, v91
	v_cvt_pk_bf16_f32 v90, v92, v93
	v_cvt_pk_bf16_f32 v91, v94, v95
	v_cvt_pk_bf16_f32 v64, v64, v65
	v_cvt_pk_bf16_f32 v65, v66, v67
	v_cvt_pk_bf16_f32 v66, v68, v69
	v_cvt_pk_bf16_f32 v67, v70, v71
	v_cvt_pk_bf16_f32 v72, v72, v73
	v_cvt_pk_bf16_f32 v73, v74, v75
	v_cvt_pk_bf16_f32 v74, v76, v77
	v_cvt_pk_bf16_f32 v75, v78, v79
	ds_read_b64_tr_b16 v[84:85], v200 offset:26624
	ds_read_b64_tr_b16 v[86:87], v200 offset:27136
	ds_read_b64_tr_b16 v[92:93], v200 offset:30720
	ds_read_b64_tr_b16 v[94:95], v200 offset:31232
	ds_read_b64_tr_b16 v[68:69], v200 offset:19456
	ds_read_b64_tr_b16 v[70:71], v200 offset:19968
	ds_read_b64_tr_b16 v[76:77], v200 offset:23552
	ds_read_b64_tr_b16 v[78:79], v200 offset:24064
	v_mfma_f32_32x32x16_bf16 v[48:63], v[218:221], v[80:83], v[48:63]
	ds_read_b64_tr_b16 v[218:219], v200 offset:27648
	ds_read_b64_tr_b16 v[220:221], v200 offset:28160
	v_mfma_f32_32x32x16_bf16 v[32:47], v[222:225], v[80:83], v[32:47]
	ds_read_b64_tr_b16 v[222:223], v200 offset:31744
	ds_read_b64_tr_b16 v[224:225], v200 offset:32256
	s_waitcnt lgkmcnt(10)
; __device__ __forceinline__ unsigned cvtpk(float lo, float hi) { f32x2_t v = {lo, hi}; bf16x2_t b = __builtin_convertvector(v, bf16x2_t); return __builtin_bit_cast(unsigned, b); }
; #define MFMA32(a, b, c) __builtin_amdgcn_mfma_f32_32x32x16_bf16((a), (b), (c), 0, 0, 0)
; template <class Prov, bool MASK>
; __device__ __forceinline__ void df_tile(const Prov& P, int comp, const bf16x8 (&qf)[4], int kv0, int kvlim, int lane, float& mx, float& ls, f32x16 (&o)[4]) {
;     ...
;     for (int ss = 0; ss < 4; ++ss) { s[0] = MFMA32(P.kfrag(comp, 0, ss, lane), qf[ss], s[0]); s[1] = MFMA32(P.kfrag(comp, 1, ss, lane), qf[ss], s[1]); }
;     if (MASK) {
; #pragma unroll
;         for (int b2 = 0; b2 < 2; ++b2)
; #pragma unroll
;             for (int r = 0; r < 16; ++r) { const int kvp = kv0 + 32 * b2 + (r & 3) + 8 * (r >> 2) + 4 * hi; if (kvp >= kvlim) s[b2][r] = -1e30f; }
;     }
;     float m = fmaxf(s[0][0], s[1][0]);
; #pragma unroll
;     for (int r = 1; r < 16; ++r) m = fmaxf(m, fmaxf(s[0][r], s[1][r]));
;     m = fmaxf(m, __shfl_xor(m, 32));
;     const float mn = fmaxf(mx, m), al = __builtin_amdgcn_exp2f(mx - mn);
;     mx = mn;
;     float ps = 0.f;
; #pragma unroll
;     for (int b2 = 0; b2 < 2; ++b2)
; #pragma unroll
;         for (int r = 0; r < 16; ++r) { const float p = __builtin_amdgcn_exp2f(s[b2][r] - mn); s[b2][r] = p; ps += p; }
;     ...
;     for (int kb = 0; kb < 4; ++kb) {
;         const int b2 = kb >> 1, r0 = 8 * (kb & 1);
;         u32x4 w; w.x = cvtpk(s[b2][r0], s[b2][r0 + 1]); w.y = cvtpk(s[b2][r0 + 2], s[b2][r0 + 3]); w.z = cvtpk(s[b2][r0 + 4], s[b2][r0 + 5]); w.w = cvtpk(s[b2][r0 + 6], s[b2][r0 + 7]);
;         const bf16x8 pf = __builtin_bit_cast(bf16x8, w);
; #pragma unroll
;         for (int c = 0; c < 4; ++c) o[c] = MFMA32(P.vfrag(kb, c, lane), pf, o[c]);
;     }
	v_mfma_f32_32x32x16_bf16 v[16:31], v[84:87], v[80:83], v[16:31]
	ds_read_b64_tr_b16 v[84:85], v200 offset:20480
	ds_read_b64_tr_b16 v[86:87], v200 offset:20992
	s_waitcnt lgkmcnt(10)
	v_mfma_f32_32x32x16_bf16 v[0:15], v[92:95], v[80:83], v[0:15]
	ds_read_b64_tr_b16 v[92:93], v200 offset:24576
	ds_read_b64_tr_b16 v[94:95], v200 offset:25088
	s_waitcnt lgkmcnt(10)
	v_mfma_f32_32x32x16_bf16 v[48:63], v[68:71], v[88:91], v[48:63]
	ds_read_b64_tr_b16 v[68:69], v200 offset:28672
	ds_read_b64_tr_b16 v[70:71], v200 offset:29184
	s_waitcnt lgkmcnt(10)
	v_mfma_f32_32x32x16_bf16 v[32:47], v[76:79], v[88:91], v[32:47]
	ds_read_b64_tr_b16 v[76:77], v200 offset:32768
	ds_read_b64_tr_b16 v[78:79], v200 offset:33280
	s_waitcnt lgkmcnt(10)
	v_mfma_f32_32x32x16_bf16 v[16:31], v[218:221], v[88:91], v[16:31]
	ds_read_b64_tr_b16 v[218:219], v200 offset:21504
	ds_read_b64_tr_b16 v[220:221], v200 offset:22016
	s_waitcnt lgkmcnt(10)
	v_mfma_f32_32x32x16_bf16 v[0:15], v[222:225], v[88:91], v[0:15]
	ds_read_b64_tr_b16 v[222:223], v200 offset:25600
	ds_read_b64_tr_b16 v[224:225], v200 offset:26112
	s_waitcnt lgkmcnt(10)
	v_mfma_f32_32x32x16_bf16 v[48:63], v[84:87], v[64:67], v[48:63]
	ds_read_b64_tr_b16 v[84:85], v200 offset:29696
	ds_read_b64_tr_b16 v[86:87], v200 offset:30208
	s_waitcnt lgkmcnt(10)
	v_mfma_f32_32x32x16_bf16 v[32:47], v[92:95], v[64:67], v[32:47]
	ds_read_b64_tr_b16 v[92:93], v200 offset:33792
	ds_read_b64_tr_b16 v[94:95], v200 offset:34304
	s_waitcnt lgkmcnt(10)
	v_mfma_f32_32x32x16_bf16 v[16:31], v[68:71], v[64:67], v[16:31]
	s_waitcnt lgkmcnt(8)
	v_mfma_f32_32x32x16_bf16 v[0:15], v[76:79], v[64:67], v[0:15]
	s_waitcnt lgkmcnt(6)
	v_mfma_f32_32x32x16_bf16 v[48:63], v[218:221], v[72:75], v[48:63]
	s_waitcnt lgkmcnt(4)
	v_mfma_f32_32x32x16_bf16 v[32:47], v[222:225], v[72:75], v[32:47]
	s_waitcnt lgkmcnt(2)
	v_mfma_f32_32x32x16_bf16 v[16:31], v[84:87], v[72:75], v[16:31]
	s_waitcnt lgkmcnt(0)
	v_mfma_f32_32x32x16_bf16 v[0:15], v[92:95], v[72:75], v[0:15]
	s_cmp_ge_u32 s36, s31
	s_cbranch_scc1 .LBB0_265
.LBB0_271:
	ds_read_b128 v[64:67], v216 offset:34816
	ds_read_b128 v[68:71], v216 offset:34848
	ds_read_b128 v[72:75], v216 offset:34880
	ds_read_b128 v[76:79], v216 offset:34912
	ds_read_b128 v[218:221], v217 offset:34816
	ds_read_b128 v[222:225], v217 offset:34848
	s_waitcnt lgkmcnt(5)
	v_mfma_f32_32x32x16_bf16 v[80:95], v[64:67], v[96:99], 0
	s_waitcnt lgkmcnt(4)
	v_mfma_f32_32x32x16_bf16 v[80:95], v[68:71], v[100:103], v[80:95]
	s_waitcnt lgkmcnt(3)
	v_mfma_f32_32x32x16_bf16 v[80:95], v[72:75], v[104:107], v[80:95]
	s_waitcnt lgkmcnt(2)
	v_mfma_f32_32x32x16_bf16 v[80:95], v[76:79], v[108:111], v[80:95]
	s_waitcnt lgkmcnt(1)
	v_mfma_f32_32x32x16_bf16 v[64:79], v[218:221], v[96:99], 0
	ds_read_b128 v[218:221], v217 offset:34880
	s_waitcnt lgkmcnt(1)
	v_mfma_f32_32x32x16_bf16 v[64:79], v[222:225], v[100:103], v[64:79]
	ds_read_b128 v[222:225], v217 offset:34912
	s_waitcnt lgkmcnt(1)
	v_mfma_f32_32x32x16_bf16 v[64:79], v[218:221], v[104:107], v[64:79]
	s_waitcnt lgkmcnt(0)
	v_mfma_f32_32x32x16_bf16 v[64:79], v[222:225], v[108:111], v[64:79]
	ds_read_b64_tr_b16 v[218:219], v201 offset:0
	ds_read_b64_tr_b16 v[220:221], v201 offset:512
	ds_read_b64_tr_b16 v[222:223], v201 offset:4096
	ds_read_b64_tr_b16 v[224:225], v201 offset:4608
	v_max3_f32 v171, v80, v81, v82
	v_max3_f32 v175, v83, v84, v85
	v_max3_f32 v171, v171, v86, v87
	v_max3_f32 v175, v175, v88, v89
	v_max3_f32 v171, v171, v90, v91
	v_max3_f32 v175, v175, v92, v93
	v_max3_f32 v171, v171, v94, v95
	s_nop 0
	v_max3_f32 v175, v175, v64, v65
	v_max3_f32 v171, v171, v66, v67
	v_max3_f32 v175, v175, v68, v69
	v_max3_f32 v171, v171, v70, v71
	v_max3_f32 v175, v175, v72, v73
	v_max3_f32 v171, v171, v74, v75
	v_max3_f32 v175, v175, v76, v77
	v_max3_f32 v171, v171, v78, v79
	v_max_f32_e32 v171, v171, v175
	ds_bpermute_b32 v175, v161, v171
	s_waitcnt lgkmcnt(0)
	v_max_f32_e32 v171, v171, v175
	v_sub_f32_e32 v175, v171, v173
	v_cmp_lt_f32_e32 vcc, 0x41000000, v175
	s_and_b64 vcc, exec, vcc
	s_cbranch_vccnz .Ldf1_rs
.Ldf1_go:
	v_sub_f32_e32 v80, v80, v173
	v_sub_f32_e32 v81, v81, v173
	v_sub_f32_e32 v82, v82, v173
	v_sub_f32_e32 v83, v83, v173
	v_sub_f32_e32 v84, v84, v173
	v_sub_f32_e32 v85, v85, v173
	v_sub_f32_e32 v86, v86, v173
	v_sub_f32_e32 v87, v87, v173
	v_exp_f32_e32 v80, v80
	v_exp_f32_e32 v81, v81
	v_exp_f32_e32 v82, v82
	v_exp_f32_e32 v83, v83
	v_exp_f32_e32 v84, v84
	v_exp_f32_e32 v85, v85
	v_exp_f32_e32 v86, v86
	v_exp_f32_e32 v87, v87
	v_sub_f32_e32 v88, v88, v173
	v_sub_f32_e32 v89, v89, v173
	v_sub_f32_e32 v90, v90, v173
	v_sub_f32_e32 v91, v91, v173
	v_sub_f32_e32 v92, v92, v173
	v_sub_f32_e32 v93, v93, v173
	v_sub_f32_e32 v94, v94, v173
	v_sub_f32_e32 v95, v95, v173
	v_exp_f32_e32 v88, v88
	v_exp_f32_e32 v89, v89
	v_exp_f32_e32 v90, v90
	v_exp_f32_e32 v91, v91
	v_exp_f32_e32 v92, v92
	v_exp_f32_e32 v93, v93
	v_exp_f32_e32 v94, v94
	v_exp_f32_e32 v95, v95
	v_add_f32_e32 v169, v169, v80
	v_add_f32_e32 v169, v169, v81
	v_add_f32_e32 v169, v169, v82
	v_add_f32_e32 v169, v169, v83
	v_add_f32_e32 v169, v169, v84
	v_add_f32_e32 v169, v169, v85
	v_add_f32_e32 v169, v169, v86
	v_add_f32_e32 v169, v169, v87
	v_sub_f32_e32 v64, v64, v173
	v_sub_f32_e32 v65, v65, v173
	v_sub_f32_e32 v66, v66, v173
	v_sub_f32_e32 v67, v67, v173
	v_sub_f32_e32 v68, v68, v173
	v_sub_f32_e32 v69, v69, v173
	v_sub_f32_e32 v70, v70, v173
	v_sub_f32_e32 v71, v71, v173
	v_exp_f32_e32 v64, v64
	v_exp_f32_e32 v65, v65
	v_exp_f32_e32 v66, v66
	v_exp_f32_e32 v67, v67
	v_exp_f32_e32 v68, v68
	v_exp_f32_e32 v69, v69
	v_exp_f32_e32 v70, v70
	v_exp_f32_e32 v71, v71
	v_add_f32_e32 v169, v169, v88
	v_add_f32_e32 v169, v169, v89
; __device__ __forceinline__ unsigned cvtpk(float lo, float hi) { f32x2_t v = {lo, hi}; bf16x2_t b = __builtin_convertvector(v, bf16x2_t); return __builtin_bit_cast(unsigned, b); }
; #define MFMA32(a, b, c) __builtin_amdgcn_mfma_f32_32x32x16_bf16((a), (b), (c), 0, 0, 0)
; template <class Prov, bool MASK>
; __device__ __forceinline__ void df_tile(const Prov& P, int comp, const bf16x8 (&qf)[4], int kv0, int kvlim, int lane, float& mx, float& ls, f32x16 (&o)[4]) {
;     ...
;     const float mn = fmaxf(mx, m), al = __builtin_amdgcn_exp2f(mx - mn);
;     mx = mn;
;     float ps = 0.f;
; #pragma unroll
;     for (int b2 = 0; b2 < 2; ++b2)
; #pragma unroll
;         for (int r = 0; r < 16; ++r) { const float p = __builtin_amdgcn_exp2f(s[b2][r] - mn); s[b2][r] = p; ps += p; }
;     ls = ls * al + ps;
; #pragma unroll
;     for (int c = 0; c < 4; ++c) o[c] = o[c] * al;
; #pragma unroll
;     for (int kb = 0; kb < 4; ++kb) {
;         const int b2 = kb >> 1, r0 = 8 * (kb & 1);
;         u32x4 w; w.x = cvtpk(s[b2][r0], s[b2][r0 + 1]); w.y = cvtpk(s[b2][r0 + 2], s[b2][r0 + 3]); w.z = cvtpk(s[b2][r0 + 4], s[b2][r0 + 5]); w.w = cvtpk(s[b2][r0 + 6], s[b2][r0 + 7]);
;         const bf16x8 pf = __builtin_bit_cast(bf16x8, w);
; #pragma unroll
;         for (int c = 0; c < 4; ++c) o[c] = MFMA32(P.vfrag(kb, c, lane), pf, o[c]);
;     }
	v_add_f32_e32 v169, v169, v90
	v_add_f32_e32 v169, v169, v91
	v_add_f32_e32 v169, v169, v92
	v_add_f32_e32 v169, v169, v93
	v_add_f32_e32 v169, v169, v94
	v_add_f32_e32 v169, v169, v95
	v_sub_f32_e32 v72, v72, v173
	v_sub_f32_e32 v73, v73, v173
	v_sub_f32_e32 v74, v74, v173
	v_sub_f32_e32 v75, v75, v173
	v_sub_f32_e32 v76, v76, v173
	v_sub_f32_e32 v77, v77, v173
	v_sub_f32_e32 v78, v78, v173
	v_sub_f32_e32 v79, v79, v173
	v_exp_f32_e32 v72, v72
	v_exp_f32_e32 v73, v73
	v_exp_f32_e32 v74, v74
	v_exp_f32_e32 v75, v75
	v_exp_f32_e32 v76, v76
	v_exp_f32_e32 v77, v77
	v_exp_f32_e32 v78, v78
	v_exp_f32_e32 v79, v79
	v_add_f32_e32 v169, v169, v64
	v_add_f32_e32 v169, v169, v65
	v_add_f32_e32 v169, v169, v66
	v_add_f32_e32 v169, v169, v67
	v_add_f32_e32 v169, v169, v68
	v_add_f32_e32 v169, v169, v69
	v_add_f32_e32 v169, v169, v70
	v_add_f32_e32 v169, v169, v71
	v_add_f32_e32 v169, v169, v72
	v_add_f32_e32 v169, v169, v73
	v_add_f32_e32 v169, v169, v74
	v_add_f32_e32 v169, v169, v75
	v_add_f32_e32 v169, v169, v76
	v_add_f32_e32 v169, v169, v77
	v_add_f32_e32 v169, v169, v78
	v_add_f32_e32 v169, v169, v79
	v_cvt_pk_bf16_f32 v80, v80, v81
	v_cvt_pk_bf16_f32 v81, v82, v83
	v_cvt_pk_bf16_f32 v82, v84, v85
	v_cvt_pk_bf16_f32 v83, v86, v87
	v_cvt_pk_bf16_f32 v88, v88, v89
	v_cvt_pk_bf16_f32 v89, v90, v91
	v_cvt_pk_bf16_f32 v90, v92, v93
	v_cvt_pk_bf16_f32 v91, v94, v95
	v_cvt_pk_bf16_f32 v64, v64, v65
	v_cvt_pk_bf16_f32 v65, v66, v67
	v_cvt_pk_bf16_f32 v66, v68, v69
	v_cvt_pk_bf16_f32 v67, v70, v71
	v_cvt_pk_bf16_f32 v72, v72, v73
	v_cvt_pk_bf16_f32 v73, v74, v75
	v_cvt_pk_bf16_f32 v74, v76, v77
	v_cvt_pk_bf16_f32 v75, v78, v79
	ds_read_b64_tr_b16 v[84:85], v201 offset:8192
	ds_read_b64_tr_b16 v[86:87], v201 offset:8704
	ds_read_b64_tr_b16 v[92:93], v201 offset:12288
	ds_read_b64_tr_b16 v[94:95], v201 offset:12800
	ds_read_b64_tr_b16 v[68:69], v201 offset:1024
	ds_read_b64_tr_b16 v[70:71], v201 offset:1536
	ds_read_b64_tr_b16 v[76:77], v201 offset:5120
	ds_read_b64_tr_b16 v[78:79], v201 offset:5632
	v_mfma_f32_32x32x16_bf16 v[48:63], v[218:221], v[80:83], v[48:63]
	ds_read_b64_tr_b16 v[218:219], v201 offset:9216
	ds_read_b64_tr_b16 v[220:221], v201 offset:9728
	v_mfma_f32_32x32x16_bf16 v[32:47], v[222:225], v[80:83], v[32:47]
	ds_read_b64_tr_b16 v[222:223], v201 offset:13312
	ds_read_b64_tr_b16 v[224:225], v201 offset:13824
	s_waitcnt lgkmcnt(10)
	v_mfma_f32_32x32x16_bf16 v[16:31], v[84:87], v[80:83], v[16:31]
	ds_read_b64_tr_b16 v[84:85], v201 offset:2048
	ds_read_b64_tr_b16 v[86:87], v201 offset:2560
	s_waitcnt lgkmcnt(10)
	v_mfma_f32_32x32x16_bf16 v[0:15], v[92:95], v[80:83], v[0:15]
	ds_read_b64_tr_b16 v[92:93], v201 offset:6144
	ds_read_b64_tr_b16 v[94:95], v201 offset:6656
	s_waitcnt lgkmcnt(10)
	v_mfma_f32_32x32x16_bf16 v[48:63], v[68:71], v[88:91], v[48:63]
	ds_read_b64_tr_b16 v[68:69], v201 offset:10240
	ds_read_b64_tr_b16 v[70:71], v201 offset:10752
	s_waitcnt lgkmcnt(10)
	v_mfma_f32_32x32x16_bf16 v[32:47], v[76:79], v[88:91], v[32:47]
	ds_read_b64_tr_b16 v[76:77], v201 offset:14336
	ds_read_b64_tr_b16 v[78:79], v201 offset:14848
	s_waitcnt lgkmcnt(10)
	v_mfma_f32_32x32x16_bf16 v[16:31], v[218:221], v[88:91], v[16:31]
	ds_read_b64_tr_b16 v[218:219], v201 offset:3072
	ds_read_b64_tr_b16 v[220:221], v201 offset:3584
	s_waitcnt lgkmcnt(10)
	v_mfma_f32_32x32x16_bf16 v[0:15], v[222:225], v[88:91], v[0:15]
	ds_read_b64_tr_b16 v[222:223], v201 offset:7168
	ds_read_b64_tr_b16 v[224:225], v201 offset:7680
	s_waitcnt lgkmcnt(10)
	v_mfma_f32_32x32x16_bf16 v[48:63], v[84:87], v[64:67], v[48:63]
	ds_read_b64_tr_b16 v[84:85], v201 offset:11264
	ds_read_b64_tr_b16 v[86:87], v201 offset:11776
	s_waitcnt lgkmcnt(10)
	v_mfma_f32_32x32x16_bf16 v[32:47], v[92:95], v[64:67], v[32:47]
	ds_read_b64_tr_b16 v[92:93], v201 offset:15360
	ds_read_b64_tr_b16 v[94:95], v201 offset:15872
	s_waitcnt lgkmcnt(10)
	v_mfma_f32_32x32x16_bf16 v[16:31], v[68:71], v[64:67], v[16:31]
	s_waitcnt lgkmcnt(8)
	v_mfma_f32_32x32x16_bf16 v[0:15], v[76:79], v[64:67], v[0:15]
	s_waitcnt lgkmcnt(6)
	v_mfma_f32_32x32x16_bf16 v[48:63], v[218:221], v[72:75], v[48:63]
	s_waitcnt lgkmcnt(4)
	v_mfma_f32_32x32x16_bf16 v[32:47], v[222:225], v[72:75], v[32:47]
	s_waitcnt lgkmcnt(2)
	v_mfma_f32_32x32x16_bf16 v[16:31], v[84:87], v[72:75], v[16:31]
	s_waitcnt lgkmcnt(0)
	v_mfma_f32_32x32x16_bf16 v[0:15], v[92:95], v[72:75], v[0:15]
	s_branch .LBB0_265
.Ldf0_rs:
	v_max_f32_e32 v171, v171, v173
	v_sub_f32_e32 v175, v173, v171
	v_exp_f32_e32 v175, v175
	v_mov_b32_e32 v173, v171
	v_mul_f32_e32 v169, v169, v175
	v_mul_f32_e32 v0, v0, v175
	v_mul_f32_e32 v1, v1, v175
	v_mul_f32_e32 v2, v2, v175
	v_mul_f32_e32 v3, v3, v175
	v_mul_f32_e32 v4, v4, v175
	v_mul_f32_e32 v5, v5, v175
	v_mul_f32_e32 v6, v6, v175
	v_mul_f32_e32 v7, v7, v175
	v_mul_f32_e32 v8, v8, v175
	v_mul_f32_e32 v9, v9, v175
	v_mul_f32_e32 v10, v10, v175
	v_mul_f32_e32 v11, v11, v175
	v_mul_f32_e32 v12, v12, v175
	v_mul_f32_e32 v13, v13, v175
	v_mul_f32_e32 v14, v14, v175
	v_mul_f32_e32 v15, v15, v175
	v_mul_f32_e32 v16, v16, v175
	v_mul_f32_e32 v17, v17, v175
	v_mul_f32_e32 v18, v18, v175
	v_mul_f32_e32 v19, v19, v175
	v_mul_f32_e32 v20, v20, v175
	v_mul_f32_e32 v21, v21, v175
	v_mul_f32_e32 v22, v22, v175
	v_mul_f32_e32 v23, v23, v175
	v_mul_f32_e32 v24, v24, v175
	v_mul_f32_e32 v25, v25, v175
	v_mul_f32_e32 v26, v26, v175
	v_mul_f32_e32 v27, v27, v175
	v_mul_f32_e32 v28, v28, v175
	v_mul_f32_e32 v29, v29, v175
	v_mul_f32_e32 v30, v30, v175
	v_mul_f32_e32 v31, v31, v175
	v_mul_f32_e32 v32, v32, v175
	v_mul_f32_e32 v33, v33, v175
	v_mul_f32_e32 v34, v34, v175
	v_mul_f32_e32 v35, v35, v175
	v_mul_f32_e32 v36, v36, v175
	v_mul_f32_e32 v37, v37, v175
	v_mul_f32_e32 v38, v38, v175
	v_mul_f32_e32 v39, v39, v175
	v_mul_f32_e32 v40, v40, v175
	v_mul_f32_e32 v41, v41, v175
	v_mul_f32_e32 v42, v42, v175
	v_mul_f32_e32 v43, v43, v175
	v_mul_f32_e32 v44, v44, v175
	v_mul_f32_e32 v45, v45, v175
	v_mul_f32_e32 v46, v46, v175
	v_mul_f32_e32 v47, v47, v175
	v_mul_f32_e32 v48, v48, v175
	v_mul_f32_e32 v49, v49, v175
	v_mul_f32_e32 v50, v50, v175
	v_mul_f32_e32 v51, v51, v175
	v_mul_f32_e32 v52, v52, v175
	v_mul_f32_e32 v53, v53, v175
	v_mul_f32_e32 v54, v54, v175
	v_mul_f32_e32 v55, v55, v175
	v_mul_f32_e32 v56, v56, v175
	v_mul_f32_e32 v57, v57, v175
	v_mul_f32_e32 v58, v58, v175
	v_mul_f32_e32 v59, v59, v175
	v_mul_f32_e32 v60, v60, v175
	v_mul_f32_e32 v61, v61, v175
	v_mul_f32_e32 v62, v62, v175
	v_mul_f32_e32 v63, v63, v175
	s_branch .Ldf0_go
